# S5 scan token loops: per-token dependent accumulate chains of neighbouring tokens interleaved (temporaries renamed, list-scheduled, bit-identical)
# speedup vs baseline: 1.0108x; 1.0051x over previous
; #define LAS __attribute__((address_space(3)))
; template <bool PASSB>
; DI void s5_pass(const int tid, LAS unsigned char* lds, const P& p, int G, int c0) {
;     ...
;             for (int t = 0; t < 16; ++t) {
;                 float bur = 0.f, bui = 0.f;
; #pragma unroll
;                 for (int k = 0; k < 4; ++k) { const f32x4 u = *(const LAS f32x4*)(ubuf + t * 16 + k * 4);
; #pragma unroll
;                     for (int e = 0; e < 4; ++e) { bur += bre[4 * k + e] * u[e]; bui += bim[4 * k + e] * u[e]; } }
;                 const float nr = are * hre - aim * him + bur, ni = are * him + aim * hre + bui; hre = nr; him = ni;
;                 if (PASSB) { hbuf[t * 136 + lane] = f2bf(hre); hbuf[t * 136 + 64 + lane] = f2bf(-him); }
.LBB0_576:
	v_add_u32_e32 v33, s0, v77
	v_pk_mul_f32 v[184:185], v[36:37], v[74:75] op_sel:[0,1]
	v_add_u32_e32 v91, v77, v32
	ds_read_b128 v[114:117], v33
	ds_read_b128 v[118:121], v33 offset:16
	ds_read_b128 v[122:125], v33 offset:32
	ds_read_b128 v[126:129], v33 offset:48
	ds_read_b128 v[130:133], v33 offset:64
	ds_read_b128 v[134:137], v33 offset:80
	ds_read_b128 v[138:141], v33 offset:96
	ds_read_b128 v[142:145], v33 offset:112
	ds_read_b128 v[150:153], v33 offset:128
	ds_read_b128 v[154:157], v33 offset:144
	ds_read_b128 v[158:161], v33 offset:160
	ds_read_b128 v[162:165], v33 offset:176
	v_pk_fma_f32 v[94:95], v[60:61], v[74:75], v[184:185] neg_lo:[0,0,1] neg_hi:[0,0,1]
	v_pk_fma_f32 v[74:75], v[60:61], v[74:75], v[184:185] op_sel_hi:[1,0,1]
	s_waitcnt lgkmcnt(11)
	v_pk_fma_f32 v[186:187], v[12:13], v[114:115], 0 op_sel_hi:[1,0,0]
	v_add_u32_e32 v32, 0x880, v32
	v_mov_b32_e32 v95, v75
	v_pk_fma_f32 v[188:189], v[38:39], v[114:115], v[186:187] op_sel:[0,1,0]
	s_waitcnt lgkmcnt(7)
	v_pk_fma_f32 v[190:191], v[12:13], v[130:131], 0 op_sel_hi:[1,0,0]
	v_pk_fma_f32 v[192:193], v[14:15], v[116:117], v[188:189] op_sel_hi:[1,0,1]
	v_pk_fma_f32 v[194:195], v[38:39], v[130:131], v[190:191] op_sel:[0,1,0]
	s_waitcnt lgkmcnt(3)
	v_pk_fma_f32 v[196:197], v[12:13], v[150:151], 0 op_sel_hi:[1,0,0]
	v_pk_fma_f32 v[198:199], v[72:73], v[116:117], v[192:193] op_sel:[0,1,0]
	v_pk_fma_f32 v[200:201], v[14:15], v[132:133], v[194:195] op_sel_hi:[1,0,1]
	ds_read_b128 v[114:117], v33 offset:192
	v_pk_fma_f32 v[202:203], v[8:9], v[118:119], v[198:199] op_sel_hi:[1,0,1]
	v_pk_fma_f32 v[204:205], v[72:73], v[132:133], v[200:201] op_sel:[0,1,0]
	v_pk_fma_f32 v[206:207], v[38:39], v[150:151], v[196:197] op_sel:[0,1,0]
	v_pk_fma_f32 v[208:209], v[70:71], v[118:119], v[202:203] op_sel:[0,1,0]
	v_pk_fma_f32 v[210:211], v[8:9], v[134:135], v[204:205] op_sel_hi:[1,0,1]
	v_pk_fma_f32 v[212:213], v[14:15], v[152:153], v[206:207] op_sel_hi:[1,0,1]
	v_pk_fma_f32 v[214:215], v[10:11], v[120:121], v[208:209] op_sel_hi:[1,0,1]
	v_pk_fma_f32 v[216:217], v[70:71], v[134:135], v[210:211] op_sel:[0,1,0]
	v_pk_fma_f32 v[218:219], v[72:73], v[152:153], v[212:213] op_sel:[0,1,0]
	v_pk_fma_f32 v[220:221], v[40:41], v[120:121], v[214:215] op_sel:[0,1,0]
	v_pk_fma_f32 v[222:223], v[10:11], v[136:137], v[216:217] op_sel_hi:[1,0,1]
	ds_read_b128 v[118:121], v33 offset:208
	v_pk_fma_f32 v[224:225], v[4:5], v[122:123], v[220:221] op_sel_hi:[1,0,1]
	v_pk_fma_f32 v[226:227], v[40:41], v[136:137], v[222:223] op_sel:[0,1,0]
	s_waitcnt lgkmcnt(4)
	v_pk_fma_f32 v[228:229], v[8:9], v[154:155], v[218:219] op_sel_hi:[1,0,1]
	v_pk_fma_f32 v[238:239], v[42:43], v[122:123], v[224:225] op_sel:[0,1,0]
	v_pk_fma_f32 v[240:241], v[4:5], v[138:139], v[226:227] op_sel_hi:[1,0,1]
	s_waitcnt lgkmcnt(1)
	v_pk_fma_f32 v[242:243], v[12:13], v[114:115], 0 op_sel_hi:[1,0,0]
	v_pk_fma_f32 v[244:245], v[6:7], v[124:125], v[238:239] op_sel_hi:[1,0,1]
	v_pk_fma_f32 v[246:247], v[42:43], v[138:139], v[240:241] op_sel:[0,1,0]
	v_pk_fma_f32 v[248:249], v[70:71], v[154:155], v[228:229] op_sel:[0,1,0]
	v_pk_fma_f32 v[184:185], v[44:45], v[124:125], v[244:245] op_sel:[0,1,0]
	v_pk_fma_f32 v[186:187], v[6:7], v[140:141], v[246:247] op_sel_hi:[1,0,1]
	v_pk_fma_f32 v[188:189], v[38:39], v[114:115], v[242:243] op_sel:[0,1,0]
	v_pk_fma_f32 v[190:191], v[0:1], v[126:127], v[184:185] op_sel_hi:[1,0,1]
	v_pk_fma_f32 v[192:193], v[10:11], v[156:157], v[248:249] op_sel_hi:[1,0,1]
	ds_read_b128 v[122:125], v33 offset:224
	v_pk_fma_f32 v[194:195], v[46:47], v[126:127], v[190:191] op_sel:[0,1,0]
	v_pk_fma_f32 v[198:199], v[44:45], v[140:141], v[186:187] op_sel:[0,1,0]
	v_pk_fma_f32 v[200:201], v[14:15], v[116:117], v[188:189] op_sel_hi:[1,0,1]
	v_pk_fma_f32 v[196:197], v[2:3], v[128:129], v[194:195] op_sel_hi:[1,0,1]
	v_pk_fma_f32 v[202:203], v[40:41], v[156:157], v[192:193] op_sel:[0,1,0]
	v_pk_fma_f32 v[204:205], v[0:1], v[142:143], v[198:199] op_sel_hi:[1,0,1]
	v_pk_fma_f32 v[206:207], v[68:69], v[128:129], v[196:197] op_sel:[0,1,0]
	ds_read_b128 v[126:129], v33 offset:240
	ds_read_b128 v[130:133], v33 offset:256
	v_pk_add_f32 v[208:209], v[94:95], v[206:207]
	v_pk_fma_f32 v[210:211], v[72:73], v[116:117], v[200:201] op_sel:[0,1,0]
	v_pk_fma_f32 v[212:213], v[4:5], v[158:159], v[202:203] op_sel_hi:[1,0,1]
	v_cvt_pk_bf16_f32 v74, v208, s0
	v_pk_mul_f32 v[214:215], v[36:37], v[208:209] op_sel:[0,1]
	v_pk_fma_f32 v[216:217], v[46:47], v[142:143], v[204:205] op_sel:[0,1,0]
	ds_write_b16 v91, v74
	s_waitcnt lgkmcnt(4)
	v_pk_fma_f32 v[220:221], v[8:9], v[118:119], v[210:211] op_sel_hi:[1,0,1]
	v_cvt_pk_bf16_f32 v74, -v209, s0
	v_pk_fma_f32 v[222:223], v[42:43], v[158:159], v[212:213] op_sel:[0,1,0]
	v_pk_fma_f32 v[218:219], v[2:3], v[144:145], v[216:217] op_sel_hi:[1,0,1]
	v_pk_fma_f32 v[224:225], v[60:61], v[208:209], v[214:215] op_sel_hi:[1,0,1]
	v_pk_fma_f32 v[226:227], v[70:71], v[118:119], v[220:221] op_sel:[0,1,0]
	ds_write_b16 v91, v74 offset:128
	v_pk_fma_f32 v[94:95], v[60:61], v[208:209], v[214:215] neg_lo:[0,0,1] neg_hi:[0,0,1]
	v_pk_fma_f32 v[238:239], v[6:7], v[160:161], v[222:223] op_sel_hi:[1,0,1]
	v_pk_fma_f32 v[74:75], v[68:69], v[144:145], v[218:219] op_sel:[0,1,0]
	v_mov_b32_e32 v95, v225
	ds_read_b128 v[134:137], v33 offset:272
	v_pk_fma_f32 v[240:241], v[10:11], v[120:121], v[226:227] op_sel_hi:[1,0,1]
	ds_read_b128 v[138:141], v33 offset:288
	v_pk_fma_f32 v[228:229], v[44:45], v[160:161], v[238:239] op_sel:[0,1,0]
	v_pk_add_f32 v[244:245], v[94:95], v[74:75]
	ds_read_b128 v[142:145], v33 offset:304
	ds_read_b128 v[150:153], v33 offset:320
	v_pk_fma_f32 v[246:247], v[40:41], v[120:121], v[240:241] op_sel:[0,1,0]
	s_waitcnt lgkmcnt(6)
; #define LAS __attribute__((address_space(3)))
; template <bool PASSB>
; DI void s5_pass(const int tid, LAS unsigned char* lds, const P& p, int G, int c0) {
;     ...
;             for (int t = 0; t < 16; ++t) {
;                 float bur = 0.f, bui = 0.f;
; #pragma unroll
;                 for (int k = 0; k < 4; ++k) { const f32x4 u = *(const LAS f32x4*)(ubuf + t * 16 + k * 4);
; #pragma unroll
;                     for (int e = 0; e < 4; ++e) { bur += bre[4 * k + e] * u[e]; bui += bim[4 * k + e] * u[e]; } }
;                 const float nr = are * hre - aim * him + bur, ni = are * him + aim * hre + bui; hre = nr; him = ni;
;                 if (PASSB) { hbuf[t * 136 + lane] = f2bf(hre); hbuf[t * 136 + 64 + lane] = f2bf(-him); }
	v_pk_fma_f32 v[242:243], v[12:13], v[130:131], 0 op_sel_hi:[1,0,0]
	v_pk_fma_f32 v[184:185], v[0:1], v[162:163], v[228:229] op_sel_hi:[1,0,1]
	v_cvt_pk_bf16_f32 v74, v244, s0
	v_pk_fma_f32 v[248:249], v[4:5], v[122:123], v[246:247] op_sel_hi:[1,0,1]
	v_pk_fma_f32 v[190:191], v[38:39], v[130:131], v[242:243] op_sel:[0,1,0]
	v_pk_mul_f32 v[186:187], v[36:37], v[244:245] op_sel:[0,1]
	v_pk_fma_f32 v[188:189], v[46:47], v[162:163], v[184:185] op_sel:[0,1,0]
	ds_write_b16 v91, v74 offset:272
	v_cvt_pk_bf16_f32 v74, -v245, s0
	v_pk_fma_f32 v[194:195], v[42:43], v[122:123], v[248:249] op_sel:[0,1,0]
	v_pk_fma_f32 v[192:193], v[14:15], v[132:133], v[190:191] op_sel_hi:[1,0,1]
	v_pk_fma_f32 v[198:199], v[2:3], v[164:165], v[188:189] op_sel_hi:[1,0,1]
	v_pk_fma_f32 v[196:197], v[60:61], v[244:245], v[186:187] op_sel_hi:[1,0,1]
	ds_write_b16 v91, v74 offset:400
	v_pk_fma_f32 v[94:95], v[60:61], v[244:245], v[186:187] neg_lo:[0,0,1] neg_hi:[0,0,1]
	v_pk_fma_f32 v[206:207], v[6:7], v[124:125], v[194:195] op_sel_hi:[1,0,1]
	v_pk_fma_f32 v[200:201], v[72:73], v[132:133], v[192:193] op_sel:[0,1,0]
	v_pk_fma_f32 v[74:75], v[68:69], v[164:165], v[198:199] op_sel:[0,1,0]
	v_mov_b32_e32 v95, v197
	ds_read_b128 v[154:157], v33 offset:336
	ds_read_b128 v[158:161], v33 offset:352
	v_pk_fma_f32 v[202:203], v[44:45], v[124:125], v[206:207] op_sel:[0,1,0]
	s_waitcnt lgkmcnt(7)
	v_pk_fma_f32 v[204:205], v[8:9], v[134:135], v[200:201] op_sel_hi:[1,0,1]
	v_pk_add_f32 v[210:211], v[94:95], v[74:75]
	ds_read_b128 v[162:165], v33 offset:368
	ds_read_b128 v[114:117], v33 offset:384
	s_waitcnt lgkmcnt(6)
	v_pk_fma_f32 v[212:213], v[12:13], v[150:151], 0 op_sel_hi:[1,0,0]
	v_pk_fma_f32 v[216:217], v[0:1], v[126:127], v[202:203] op_sel_hi:[1,0,1]
	v_pk_fma_f32 v[220:221], v[70:71], v[134:135], v[204:205] op_sel:[0,1,0]
	v_cvt_pk_bf16_f32 v74, v210, s0
	v_pk_fma_f32 v[208:209], v[38:39], v[150:151], v[212:213] op_sel:[0,1,0]
	v_pk_fma_f32 v[214:215], v[46:47], v[126:127], v[216:217] op_sel:[0,1,0]
	v_pk_fma_f32 v[222:223], v[10:11], v[136:137], v[220:221] op_sel_hi:[1,0,1]
	ds_write_b16 v91, v74 offset:544
	v_cvt_pk_bf16_f32 v74, -v211, s0
	v_pk_fma_f32 v[218:219], v[14:15], v[152:153], v[208:209] op_sel_hi:[1,0,1]
	v_pk_fma_f32 v[224:225], v[2:3], v[128:129], v[214:215] op_sel_hi:[1,0,1]
	v_pk_fma_f32 v[226:227], v[40:41], v[136:137], v[222:223] op_sel:[0,1,0]
	ds_write_b16 v91, v74 offset:672
	ds_read_b128 v[118:121], v33 offset:400
	v_pk_fma_f32 v[238:239], v[72:73], v[152:153], v[218:219] op_sel:[0,1,0]
	v_pk_fma_f32 v[74:75], v[68:69], v[128:129], v[224:225] op_sel:[0,1,0]
	ds_read_b128 v[122:125], v33 offset:416
	v_pk_fma_f32 v[240:241], v[4:5], v[138:139], v[226:227] op_sel_hi:[1,0,1]
	v_pk_mul_f32 v[228:229], v[36:37], v[210:211] op_sel:[0,1]
	ds_read_b128 v[126:129], v33 offset:432
	ds_read_b128 v[130:133], v33 offset:448
	s_waitcnt lgkmcnt(9)
	v_pk_fma_f32 v[246:247], v[8:9], v[154:155], v[238:239] op_sel_hi:[1,0,1]
	v_pk_fma_f32 v[242:243], v[42:43], v[138:139], v[240:241] op_sel:[0,1,0]
	v_pk_fma_f32 v[184:185], v[60:61], v[210:211], v[228:229] op_sel_hi:[1,0,1]
	s_waitcnt lgkmcnt(6)
	v_pk_fma_f32 v[248:249], v[12:13], v[114:115], 0 op_sel_hi:[1,0,0]
	v_pk_fma_f32 v[190:191], v[70:71], v[154:155], v[246:247] op_sel:[0,1,0]
	v_pk_fma_f32 v[94:95], v[60:61], v[210:211], v[228:229] neg_lo:[0,0,1] neg_hi:[0,0,1]
	v_pk_fma_f32 v[188:189], v[6:7], v[140:141], v[242:243] op_sel_hi:[1,0,1]
	v_mov_b32_e32 v95, v185
	v_pk_fma_f32 v[244:245], v[38:39], v[114:115], v[248:249] op_sel:[0,1,0]
	v_pk_fma_f32 v[186:187], v[10:11], v[156:157], v[190:191] op_sel_hi:[1,0,1]
	v_pk_fma_f32 v[194:195], v[44:45], v[140:141], v[188:189] op_sel:[0,1,0]
	v_pk_add_f32 v[192:193], v[94:95], v[74:75]
	v_pk_fma_f32 v[198:199], v[14:15], v[116:117], v[244:245] op_sel_hi:[1,0,1]
	v_pk_fma_f32 v[196:197], v[40:41], v[156:157], v[186:187] op_sel:[0,1,0]
	v_pk_fma_f32 v[206:207], v[0:1], v[142:143], v[194:195] op_sel_hi:[1,0,1]
	v_cvt_pk_bf16_f32 v74, v192, s0
	v_pk_fma_f32 v[200:201], v[72:73], v[116:117], v[198:199] op_sel:[0,1,0]
	ds_read_b128 v[134:137], v33 offset:464
	v_pk_fma_f32 v[202:203], v[4:5], v[158:159], v[196:197] op_sel_hi:[1,0,1]
	v_pk_mul_f32 v[204:205], v[36:37], v[192:193] op_sel:[0,1]
	v_pk_fma_f32 v[212:213], v[46:47], v[142:143], v[206:207] op_sel:[0,1,0]
	ds_write_b16 v91, v74 offset:816
	s_waitcnt lgkmcnt(5)
	v_pk_fma_f32 v[216:217], v[8:9], v[118:119], v[200:201] op_sel_hi:[1,0,1]
	s_waitcnt lgkmcnt(2)
	v_pk_fma_f32 v[220:221], v[12:13], v[130:131], 0 op_sel_hi:[1,0,0]
	v_cvt_pk_bf16_f32 v74, -v193, s0
	v_pk_fma_f32 v[208:209], v[42:43], v[158:159], v[202:203] op_sel:[0,1,0]
	v_pk_fma_f32 v[214:215], v[2:3], v[144:145], v[212:213] op_sel_hi:[1,0,1]
	v_pk_fma_f32 v[222:223], v[60:61], v[192:193], v[204:205] op_sel_hi:[1,0,1]
	v_pk_fma_f32 v[218:219], v[70:71], v[118:119], v[216:217] op_sel:[0,1,0]
	v_pk_fma_f32 v[224:225], v[38:39], v[130:131], v[220:221] op_sel:[0,1,0]
	ds_write_b16 v91, v74 offset:944
	v_pk_fma_f32 v[94:95], v[60:61], v[192:193], v[204:205] neg_lo:[0,0,1] neg_hi:[0,0,1]
	v_pk_fma_f32 v[226:227], v[6:7], v[160:161], v[208:209] op_sel_hi:[1,0,1]
	v_pk_fma_f32 v[74:75], v[68:69], v[144:145], v[214:215] op_sel:[0,1,0]
	v_mov_b32_e32 v95, v223
	v_pk_fma_f32 v[238:239], v[10:11], v[120:121], v[218:219] op_sel_hi:[1,0,1]
	v_pk_fma_f32 v[240:241], v[14:15], v[132:133], v[224:225] op_sel_hi:[1,0,1]
	v_pk_fma_f32 v[246:247], v[44:45], v[160:161], v[226:227] op_sel:[0,1,0]
	v_pk_add_f32 v[210:211], v[94:95], v[74:75]
	v_pk_fma_f32 v[228:229], v[40:41], v[120:121], v[238:239] op_sel:[0,1,0]
	v_pk_fma_f32 v[242:243], v[72:73], v[132:133], v[240:241] op_sel:[0,1,0]
	ds_read_b128 v[138:141], v33 offset:480
	v_pk_fma_f32 v[184:185], v[0:1], v[162:163], v[246:247] op_sel_hi:[1,0,1]
	v_cvt_pk_bf16_f32 v74, v210, s0
	v_pk_fma_f32 v[248:249], v[4:5], v[122:123], v[228:229] op_sel_hi:[1,0,1]
	s_waitcnt lgkmcnt(3)
; #define LAS __attribute__((address_space(3)))
; template <bool PASSB>
; DI void s5_pass(const int tid, LAS unsigned char* lds, const P& p, int G, int c0) {
;     ...
;             for (int t = 0; t < 16; ++t) {
;                 float bur = 0.f, bui = 0.f;
; #pragma unroll
;                 for (int k = 0; k < 4; ++k) { const f32x4 u = *(const LAS f32x4*)(ubuf + t * 16 + k * 4);
; #pragma unroll
;                     for (int e = 0; e < 4; ++e) { bur += bre[4 * k + e] * u[e]; bui += bim[4 * k + e] * u[e]; } }
;                 const float nr = are * hre - aim * him + bur, ni = are * him + aim * hre + bui; hre = nr; him = ni;
;                 if (PASSB) { hbuf[t * 136 + lane] = f2bf(hre); hbuf[t * 136 + 64 + lane] = f2bf(-him); }
	v_pk_fma_f32 v[190:191], v[8:9], v[134:135], v[242:243] op_sel_hi:[1,0,1]
	v_pk_mul_f32 v[188:189], v[36:37], v[210:211] op_sel:[0,1]
	v_pk_fma_f32 v[244:245], v[46:47], v[162:163], v[184:185] op_sel:[0,1,0]
	ds_write_b16 v91, v74 offset:1088
	v_cvt_pk_bf16_f32 v74, -v211, s0
	v_pk_fma_f32 v[186:187], v[42:43], v[122:123], v[248:249] op_sel:[0,1,0]
	v_pk_fma_f32 v[194:195], v[70:71], v[134:135], v[190:191] op_sel:[0,1,0]
	v_pk_fma_f32 v[198:199], v[2:3], v[164:165], v[244:245] op_sel_hi:[1,0,1]
	v_pk_fma_f32 v[196:197], v[60:61], v[210:211], v[188:189] op_sel_hi:[1,0,1]
	ds_write_b16 v91, v74 offset:1216
	v_pk_fma_f32 v[94:95], v[60:61], v[210:211], v[188:189] neg_lo:[0,0,1] neg_hi:[0,0,1]
	v_pk_fma_f32 v[206:207], v[6:7], v[124:125], v[186:187] op_sel_hi:[1,0,1]
	v_pk_fma_f32 v[200:201], v[10:11], v[136:137], v[194:195] op_sel_hi:[1,0,1]
	v_pk_fma_f32 v[74:75], v[68:69], v[164:165], v[198:199] op_sel:[0,1,0]
	v_mov_b32_e32 v95, v197
	v_pk_fma_f32 v[202:203], v[44:45], v[124:125], v[206:207] op_sel:[0,1,0]
	v_pk_fma_f32 v[212:213], v[40:41], v[136:137], v[200:201] op_sel:[0,1,0]
	ds_read_b128 v[142:145], v33 offset:496
	v_pk_add_f32 v[216:217], v[94:95], v[74:75]
	v_pk_fma_f32 v[220:221], v[0:1], v[126:127], v[202:203] op_sel_hi:[1,0,1]
	s_waitcnt lgkmcnt(3)
	v_pk_fma_f32 v[192:193], v[4:5], v[138:139], v[212:213] op_sel_hi:[1,0,1]
	v_cvt_pk_bf16_f32 v74, v216, s0
	v_pk_mul_f32 v[204:205], v[36:37], v[216:217] op_sel:[0,1]
	v_pk_fma_f32 v[208:209], v[46:47], v[126:127], v[220:221] op_sel:[0,1,0]
	v_pk_fma_f32 v[214:215], v[42:43], v[138:139], v[192:193] op_sel:[0,1,0]
	ds_write_b16 v91, v74 offset:1360
	v_cvt_pk_bf16_f32 v74, -v217, s0
	v_pk_fma_f32 v[222:223], v[2:3], v[128:129], v[208:209] op_sel_hi:[1,0,1]
	v_pk_fma_f32 v[218:219], v[60:61], v[216:217], v[204:205] op_sel_hi:[1,0,1]
	v_pk_fma_f32 v[224:225], v[6:7], v[140:141], v[214:215] op_sel_hi:[1,0,1]
	ds_write_b16 v91, v74 offset:1488
	v_pk_fma_f32 v[94:95], v[60:61], v[216:217], v[204:205] neg_lo:[0,0,1] neg_hi:[0,0,1]
	v_pk_fma_f32 v[74:75], v[68:69], v[128:129], v[222:223] op_sel:[0,1,0]
	v_mov_b32_e32 v95, v219
	v_pk_fma_f32 v[226:227], v[44:45], v[140:141], v[224:225] op_sel:[0,1,0]
	v_pk_add_f32 v[238:239], v[94:95], v[74:75]
	s_waitcnt lgkmcnt(2)
	v_pk_fma_f32 v[240:241], v[0:1], v[142:143], v[226:227] op_sel_hi:[1,0,1]
	v_pk_mul_f32 v[246:247], v[36:37], v[238:239] op_sel:[0,1]
	v_pk_fma_f32 v[228:229], v[46:47], v[142:143], v[240:241] op_sel:[0,1,0]
	v_cvt_pk_bf16_f32 v74, v238, s0
	v_pk_fma_f32 v[242:243], v[60:61], v[238:239], v[246:247] op_sel_hi:[1,0,1]
	v_pk_fma_f32 v[184:185], v[2:3], v[144:145], v[228:229] op_sel_hi:[1,0,1]
	ds_write_b16 v91, v74 offset:1632
	v_cvt_pk_bf16_f32 v74, -v239, s0
	v_pk_fma_f32 v[94:95], v[60:61], v[238:239], v[246:247] neg_lo:[0,0,1] neg_hi:[0,0,1]
	v_pk_fma_f32 v[248:249], v[68:69], v[144:145], v[184:185] op_sel:[0,1,0]
	v_mov_b32_e32 v95, v243
	ds_write_b16 v91, v74 offset:1760
	v_pk_add_f32 v[74:75], v[94:95], v[248:249]
	s_nop 0
	v_cvt_pk_bf16_f32 v33, v74, s0
	ds_write_b16 v91, v33 offset:1904
	v_cvt_pk_bf16_f32 v33, -v75, s0
	s_addk_i32 s0, 0x200
	s_cmpk_lg_i32 s0, 0x400
	ds_write_b16 v91, v33 offset:2032
	s_cbranch_scc1 .LBB0_576
; #define LAS __attribute__((address_space(3)))
; DI float gelu_tanh(float x) { float u = 0.7978845608028654f * (x + 0.044715f * x * x * x); float e = __expf(2.f * u); float th = 1.f - 2.f / (e + 1.f); return 0.5f * x * (1.f + th); }
; DI f32x4 mfma16(bf16x8 a, bf16x8 b, f32x4 c) { return __builtin_amdgcn_mfma_f32_16x16x32_bf16(a, b, c, 0, 0, 0); }
; DI void lds_wait() { asm volatile("s_waitcnt lgkmcnt(0)" ::: "memory"); }
; template <bool PASSB>
; DI void s5_pass(const int tid, LAS unsigned char* lds, const P& p, int G, int c0) {
;     ...
;             if (PASSB) {
;                 lds_wait();
;                 f32x4 acc = (f32x4){0.f, 0.f, 0.f, 0.f};
; #pragma unroll
;                 for (int ks = 0; ks < 4; ++ks) { const bf16x8 a = *(const LAS bf16x8*)(hbuf + fr * 136 + ks * 32 + fq * 8); acc = mfma16(a, cf[ks], acc); }
; #pragma unroll
;                 for (int j = 0; j < 4; ++j) { const int tk = fq * 4 + j; const float y = acc[j] + dsk * ubuf[tk * 16 + fr];
;                     zs5[(tokbase + tile * 16 + tk) * 256 + g * 16 + fr] = f2bf(gelu_tanh(y)); }
;             }
	s_waitcnt lgkmcnt(0)
	v_add_u32_e32 v91, v80, v48
	ds_read_b128 v[32:35], v91 offset:1024
	ds_read_b128 v[92:95], v91 offset:1088
	s_lshl_b32 s0, s8, 4
	s_add_i32 s8, s8, 1
	s_cmp_eq_u32 s8, 16
	s_waitcnt vmcnt(4) lgkmcnt(1)
	v_mfma_f32_16x16x32_bf16 v[32:35], v[32:35], v[16:19], 0
	s_waitcnt vmcnt(3) lgkmcnt(0)
	v_mfma_f32_16x16x32_bf16 v[32:35], v[92:95], v[20:23], v[32:35]
	ds_read_b128 v[92:95], v91 offset:1152
	s_waitcnt vmcnt(2) lgkmcnt(0)
	v_mfma_f32_16x16x32_bf16 v[32:35], v[92:95], v[24:27], v[32:35]
	ds_read_b128 v[92:95], v91 offset:1216
	ds_read_b32 v91, v86
	s_waitcnt vmcnt(1) lgkmcnt(1)
	v_mfma_f32_16x16x32_bf16 v[32:35], v[92:95], v[28:31], v[32:35]
	s_waitcnt vmcnt(0) lgkmcnt(0)
	s_nop 6
	v_fma_f32 v32, v90, v91, v32
	v_mul_f32_e32 v91, 0x3d372713, v32
	v_mul_f32_e32 v91, v32, v91
	v_fma_f32 v91, v32, v91, v32
	v_mul_f32_e32 v91, 0x3f4c422a, v91
	v_add_f32_e32 v91, v91, v91
	v_mul_f32_e32 v91, 0x3fb8aa3b, v91
	v_exp_f32_e32 v91, v91
	v_mul_f32_e32 v32, 0.5, v32
	v_add_f32_e32 v91, 1.0, v91
	v_div_scale_f32 v92, s[10:11], v91, v91, 2.0
	v_rcp_f32_e32 v93, v92
	s_nop 0
	v_fma_f32 v94, -v92, v93, 1.0
	v_fmac_f32_e32 v93, v94, v93
	v_div_scale_f32 v94, vcc, 2.0, v91, 2.0
	v_mul_f32_e32 v95, v94, v93
	v_fma_f32 v96, -v92, v95, v94
	v_fmac_f32_e32 v95, v96, v93
	v_fma_f32 v92, -v92, v95, v94
	v_div_fmas_f32 v92, v92, v93, v95
	v_div_fixup_f32 v91, v92, v91, 2.0
	v_sub_f32_e32 v91, 1.0, v91
	v_add_f32_e32 v91, 1.0, v91
	v_or3_b32 v92, s0, v81, v62
	v_mov_b32_e32 v93, v63
	v_mul_f32_e32 v32, v32, v91
	v_lshlrev_b64 v[92:93], 9, v[92:93]
	v_cvt_pk_bf16_f32 v32, v32, s0
	v_lshl_add_u64 v[92:93], v[66:67], 0, v[92:93]
	global_store_short v[92:93], v32, off
	ds_read_b32 v32, v87
	s_waitcnt lgkmcnt(0)
	v_fma_f32 v32, v90, v32, v33
	v_mul_f32_e32 v33, 0x3d372713, v32
	v_mul_f32_e32 v33, v32, v33
	v_fma_f32 v33, v32, v33, v32
	v_mul_f32_e32 v33, 0x3f4c422a, v33
	v_add_f32_e32 v33, v33, v33
	v_mul_f32_e32 v33, 0x3fb8aa3b, v33
	v_exp_f32_e32 v33, v33
	v_mul_f32_e32 v32, 0.5, v32
	v_add_f32_e32 v33, 1.0, v33
	v_div_scale_f32 v91, s[10:11], v33, v33, 2.0
	v_rcp_f32_e32 v92, v91
	s_nop 0
	v_fma_f32 v93, -v91, v92, 1.0
	v_fmac_f32_e32 v92, v93, v92
	v_div_scale_f32 v93, vcc, 2.0, v33, 2.0
	v_mul_f32_e32 v94, v93, v92
	v_fma_f32 v95, -v91, v94, v93
	v_fmac_f32_e32 v94, v95, v92
	v_fma_f32 v91, -v91, v94, v93
	v_div_fmas_f32 v91, v91, v92, v94
	v_div_fixup_f32 v33, v91, v33, 2.0
	v_sub_f32_e32 v33, 1.0, v33
	v_add_f32_e32 v33, 1.0, v33
	v_mul_f32_e32 v32, v32, v33
	v_cvt_pk_bf16_f32 v91, v32, s0
	v_or3_b32 v32, s0, v82, v62
	v_mov_b32_e32 v33, v63
	v_lshlrev_b64 v[32:33], 9, v[32:33]
	v_lshl_add_u64 v[32:33], v[66:67], 0, v[32:33]
	global_store_short v[32:33], v91, off
	ds_read_b32 v32, v88
	s_waitcnt lgkmcnt(0)
	v_fma_f32 v32, v90, v32, v34
	v_mul_f32_e32 v33, 0x3d372713, v32
	v_mul_f32_e32 v33, v32, v33
	v_fma_f32 v33, v32, v33, v32
	v_mul_f32_e32 v33, 0x3f4c422a, v33
	v_add_f32_e32 v33, v33, v33
	v_mul_f32_e32 v33, 0x3fb8aa3b, v33
	v_exp_f32_e32 v33, v33
	v_mul_f32_e32 v32, 0.5, v32
	v_add_f32_e32 v33, 1.0, v33
	v_div_scale_f32 v34, s[10:11], v33, v33, 2.0
	v_rcp_f32_e32 v91, v34
	s_nop 0
	v_fma_f32 v92, -v34, v91, 1.0
	v_fmac_f32_e32 v91, v92, v91
	v_div_scale_f32 v92, vcc, 2.0, v33, 2.0
	v_mul_f32_e32 v93, v92, v91
	v_fma_f32 v94, -v34, v93, v92
	v_fmac_f32_e32 v93, v94, v91
	v_fma_f32 v34, -v34, v93, v92
	v_div_fmas_f32 v34, v34, v91, v93
	v_div_fixup_f32 v33, v34, v33, 2.0
	v_sub_f32_e32 v33, 1.0, v33
	v_add_f32_e32 v33, 1.0, v33
	v_mul_f32_e32 v32, v32, v33
	v_cvt_pk_bf16_f32 v34, v32, s0
	v_or3_b32 v32, s0, v83, v62
	v_mov_b32_e32 v33, v63
	v_lshlrev_b64 v[32:33], 9, v[32:33]
	v_lshl_add_u64 v[32:33], v[66:67], 0, v[32:33]
	global_store_short v[32:33], v34, off
	ds_read_b32 v32, v89
	s_waitcnt lgkmcnt(0)
	v_fmac_f32_e32 v35, v90, v32
	v_mul_f32_e32 v32, 0x3d372713, v35
	v_mul_f32_e32 v32, v35, v32
	v_fma_f32 v32, v35, v32, v35
	v_mul_f32_e32 v32, 0x3f4c422a, v32
	v_add_f32_e32 v32, v32, v32
	v_mul_f32_e32 v32, 0x3fb8aa3b, v32
	v_exp_f32_e32 v32, v32
	s_nop 0
	v_add_f32_e32 v32, 1.0, v32
	v_div_scale_f32 v33, s[10:11], v32, v32, 2.0
	v_rcp_f32_e32 v34, v33
	s_nop 0
	v_fma_f32 v91, -v33, v34, 1.0
	v_fmac_f32_e32 v34, v91, v34
	v_div_scale_f32 v91, vcc, 2.0, v32, 2.0
	v_mul_f32_e32 v92, v91, v34
	v_fma_f32 v93, -v33, v92, v91
	v_fmac_f32_e32 v92, v93, v34
	v_fma_f32 v33, -v33, v92, v91
	v_div_fmas_f32 v33, v33, v34, v92
	v_div_fixup_f32 v32, v33, v32, 2.0
	v_sub_f32_e32 v32, 1.0, v32
	v_mul_f32_e32 v33, 0.5, v35
	v_add_f32_e32 v32, 1.0, v32
	v_mul_f32_e32 v32, v33, v32
	v_cvt_pk_bf16_f32 v34, v32, s0
	v_or3_b32 v32, s0, v84, v62
	v_mov_b32_e32 v33, v63
	v_lshlrev_b64 v[32:33], 9, v[32:33]
	v_lshl_add_u64 v[32:33], v[66:67], 0, v[32:33]
	global_store_short v[32:33], v34, off
	s_waitcnt lgkmcnt(0)
	s_cbranch_scc0 .LBB0_573
	v_readlane_b32 s0, v253, 16
	s_add_i32 s12, s12, s0
	s_cmpk_gt_i32 s12, 0x1ff
	v_readlane_b32 s1, v253, 17
	s_cbranch_scc0 .LBB0_568
	s_mov_b32 s64, s13
	s_mov_b32 s67, s26
	s_mov_b32 s66, s28

; #define LAS __attribute__((address_space(3)))
; template <bool PASSB>
; DI void s5_pass(const int tid, LAS unsigned char* lds, const P& p, int G, int c0) {
;     ...
;             for (int t = 0; t < 16; ++t) {
;                 float bur = 0.f, bui = 0.f;
; #pragma unroll
;                 for (int k = 0; k < 4; ++k) { const f32x4 u = *(const LAS f32x4*)(ubuf + t * 16 + k * 4);
; #pragma unroll
;                     for (int e = 0; e < 4; ++e) { bur += bre[4 * k + e] * u[e]; bui += bim[4 * k + e] * u[e]; } }
;                 const float nr = are * hre - aim * him + bur, ni = are * him + aim * hre + bui; hre = nr; him = ni;
.LBB0_588:
	v_add_u32_e32 v25, s0, v51
	v_pk_mul_f32 v[130:131], v[46:47], v[48:49] op_sel:[0,1]
	s_addk_i32 s0, 0x200
	ds_read_b128 v[72:75], v25
	ds_read_b128 v[76:79], v25 offset:16
	ds_read_b128 v[80:83], v25 offset:32
	ds_read_b128 v[84:87], v25 offset:48
	ds_read_b128 v[88:91], v25 offset:64
	ds_read_b128 v[92:95], v25 offset:80
	ds_read_b128 v[96:99], v25 offset:96
	ds_read_b128 v[100:103], v25 offset:112
	ds_read_b128 v[104:107], v25 offset:128
	ds_read_b128 v[108:111], v25 offset:144
	ds_read_b128 v[112:115], v25 offset:160
	ds_read_b128 v[116:119], v25 offset:176
	v_pk_fma_f32 v[132:133], v[22:23], v[48:49], v[130:131] op_sel_hi:[1,0,1]
	v_pk_fma_f32 v[58:59], v[22:23], v[48:49], v[130:131] neg_lo:[0,0,1] neg_hi:[0,0,1]
	s_waitcnt lgkmcnt(11)
	v_pk_fma_f32 v[134:135], v[12:13], v[72:73], 0 op_sel_hi:[1,0,0]
	v_mov_b32_e32 v59, v133
	s_cmpk_lg_i32 s0, 0x400
	v_pk_fma_f32 v[136:137], v[44:45], v[72:73], v[134:135] op_sel:[0,1,0]
	s_waitcnt lgkmcnt(7)
	v_pk_fma_f32 v[138:139], v[12:13], v[88:89], 0 op_sel_hi:[1,0,0]
	v_pk_fma_f32 v[140:141], v[14:15], v[74:75], v[136:137] op_sel_hi:[1,0,1]
	v_pk_fma_f32 v[142:143], v[44:45], v[88:89], v[138:139] op_sel:[0,1,0]
	s_waitcnt lgkmcnt(3)
	v_pk_fma_f32 v[144:145], v[12:13], v[104:105], 0 op_sel_hi:[1,0,0]
	v_pk_fma_f32 v[146:147], v[42:43], v[74:75], v[140:141] op_sel:[0,1,0]
	v_pk_fma_f32 v[148:149], v[14:15], v[90:91], v[142:143] op_sel_hi:[1,0,1]
	ds_read_b128 v[72:75], v25 offset:192
	v_pk_fma_f32 v[150:151], v[8:9], v[76:77], v[146:147] op_sel_hi:[1,0,1]
	v_pk_fma_f32 v[152:153], v[42:43], v[90:91], v[148:149] op_sel:[0,1,0]
	v_pk_fma_f32 v[154:155], v[44:45], v[104:105], v[144:145] op_sel:[0,1,0]
	v_pk_fma_f32 v[156:157], v[40:41], v[76:77], v[150:151] op_sel:[0,1,0]
	v_pk_fma_f32 v[158:159], v[8:9], v[92:93], v[152:153] op_sel_hi:[1,0,1]
	v_pk_fma_f32 v[160:161], v[14:15], v[106:107], v[154:155] op_sel_hi:[1,0,1]
	v_pk_fma_f32 v[162:163], v[10:11], v[78:79], v[156:157] op_sel_hi:[1,0,1]
	v_pk_fma_f32 v[164:165], v[40:41], v[92:93], v[158:159] op_sel:[0,1,0]
	v_pk_fma_f32 v[166:167], v[42:43], v[106:107], v[160:161] op_sel:[0,1,0]
	v_pk_fma_f32 v[168:169], v[38:39], v[78:79], v[162:163] op_sel:[0,1,0]
	v_pk_fma_f32 v[170:171], v[10:11], v[94:95], v[164:165] op_sel_hi:[1,0,1]
	ds_read_b128 v[76:79], v25 offset:208
	v_pk_fma_f32 v[172:173], v[4:5], v[80:81], v[168:169] op_sel_hi:[1,0,1]
	v_pk_fma_f32 v[174:175], v[38:39], v[94:95], v[170:171] op_sel:[0,1,0]
	s_waitcnt lgkmcnt(4)
	v_pk_fma_f32 v[176:177], v[8:9], v[108:109], v[166:167] op_sel_hi:[1,0,1]
	v_pk_fma_f32 v[130:131], v[36:37], v[80:81], v[172:173] op_sel:[0,1,0]
	v_pk_fma_f32 v[132:133], v[4:5], v[96:97], v[174:175] op_sel_hi:[1,0,1]
	s_waitcnt lgkmcnt(1)
	v_pk_fma_f32 v[134:135], v[12:13], v[72:73], 0 op_sel_hi:[1,0,0]
	v_pk_fma_f32 v[136:137], v[6:7], v[82:83], v[130:131] op_sel_hi:[1,0,1]
	v_pk_fma_f32 v[138:139], v[36:37], v[96:97], v[132:133] op_sel:[0,1,0]
	v_pk_fma_f32 v[140:141], v[40:41], v[108:109], v[176:177] op_sel:[0,1,0]
	v_pk_fma_f32 v[142:143], v[34:35], v[82:83], v[136:137] op_sel:[0,1,0]
	v_pk_fma_f32 v[146:147], v[44:45], v[72:73], v[134:135] op_sel:[0,1,0]
	v_pk_fma_f32 v[148:149], v[6:7], v[98:99], v[138:139] op_sel_hi:[1,0,1]
	v_pk_fma_f32 v[144:145], v[0:1], v[84:85], v[142:143] op_sel_hi:[1,0,1]
	v_pk_fma_f32 v[150:151], v[10:11], v[110:111], v[140:141] op_sel_hi:[1,0,1]
	v_pk_fma_f32 v[152:153], v[14:15], v[74:75], v[146:147] op_sel_hi:[1,0,1]
	v_pk_fma_f32 v[154:155], v[32:33], v[84:85], v[144:145] op_sel:[0,1,0]
	ds_read_b128 v[80:83], v25 offset:224
	v_pk_fma_f32 v[156:157], v[34:35], v[98:99], v[148:149] op_sel:[0,1,0]
	v_pk_fma_f32 v[158:159], v[2:3], v[86:87], v[154:155] op_sel_hi:[1,0,1]
	v_pk_fma_f32 v[160:161], v[38:39], v[110:111], v[150:151] op_sel:[0,1,0]
	v_pk_fma_f32 v[162:163], v[42:43], v[74:75], v[152:153] op_sel:[0,1,0]
	v_pk_fma_f32 v[164:165], v[30:31], v[86:87], v[158:159] op_sel:[0,1,0]
	ds_read_b128 v[84:87], v25 offset:240
	ds_read_b128 v[88:91], v25 offset:256
	v_pk_fma_f32 v[168:169], v[0:1], v[100:101], v[156:157] op_sel_hi:[1,0,1]
	v_pk_fma_f32 v[170:171], v[4:5], v[112:113], v[160:161] op_sel_hi:[1,0,1]
	s_waitcnt lgkmcnt(3)
	v_pk_fma_f32 v[166:167], v[8:9], v[76:77], v[162:163] op_sel_hi:[1,0,1]
	v_pk_fma_f32 v[172:173], v[32:33], v[100:101], v[168:169] op_sel:[0,1,0]
	v_pk_fma_f32 v[174:175], v[36:37], v[112:113], v[170:171] op_sel:[0,1,0]
	v_pk_fma_f32 v[130:131], v[40:41], v[76:77], v[166:167] op_sel:[0,1,0]
	v_pk_fma_f32 v[132:133], v[2:3], v[102:103], v[172:173] op_sel_hi:[1,0,1]
	v_pk_fma_f32 v[176:177], v[6:7], v[114:115], v[174:175] op_sel_hi:[1,0,1]
	v_pk_fma_f32 v[136:137], v[10:11], v[78:79], v[130:131] op_sel_hi:[1,0,1]
	ds_read_b128 v[92:95], v25 offset:272
	v_pk_fma_f32 v[134:135], v[30:31], v[102:103], v[132:133] op_sel:[0,1,0]
	ds_read_b128 v[96:99], v25 offset:288
	v_pk_fma_f32 v[138:139], v[34:35], v[114:115], v[176:177] op_sel:[0,1,0]
	v_pk_fma_f32 v[142:143], v[38:39], v[78:79], v[136:137] op_sel:[0,1,0]
	ds_read_b128 v[100:103], v25 offset:304
	ds_read_b128 v[104:107], v25 offset:320
	v_pk_fma_f32 v[140:141], v[0:1], v[116:117], v[138:139] op_sel_hi:[1,0,1]
	s_waitcnt lgkmcnt(6)
	v_pk_fma_f32 v[146:147], v[4:5], v[80:81], v[142:143] op_sel_hi:[1,0,1]
	v_pk_add_f32 v[144:145], v[58:59], v[164:165]
	s_waitcnt lgkmcnt(4)
; #define LAS __attribute__((address_space(3)))
; template <bool PASSB>
; DI void s5_pass(const int tid, LAS unsigned char* lds, const P& p, int G, int c0) {
;     ...
;             for (int t = 0; t < 16; ++t) {
;                 float bur = 0.f, bui = 0.f;
; #pragma unroll
;                 for (int k = 0; k < 4; ++k) { const f32x4 u = *(const LAS f32x4*)(ubuf + t * 16 + k * 4);
; #pragma unroll
;                     for (int e = 0; e < 4; ++e) { bur += bre[4 * k + e] * u[e]; bui += bim[4 * k + e] * u[e]; } }
;                 const float nr = are * hre - aim * him + bur, ni = are * him + aim * hre + bui; hre = nr; him = ni;
	v_pk_fma_f32 v[148:149], v[12:13], v[88:89], 0 op_sel_hi:[1,0,0]
	v_pk_fma_f32 v[154:155], v[32:33], v[116:117], v[140:141] op_sel:[0,1,0]
	v_pk_fma_f32 v[150:151], v[36:37], v[80:81], v[146:147] op_sel:[0,1,0]
	v_pk_mul_f32 v[152:153], v[46:47], v[144:145] op_sel:[0,1]
	v_pk_fma_f32 v[158:159], v[44:45], v[88:89], v[148:149] op_sel:[0,1,0]
	v_pk_fma_f32 v[156:157], v[2:3], v[118:119], v[154:155] op_sel_hi:[1,0,1]
	v_pk_fma_f32 v[160:161], v[6:7], v[82:83], v[150:151] op_sel_hi:[1,0,1]
	v_pk_fma_f32 v[162:163], v[22:23], v[144:145], v[152:153] op_sel_hi:[1,0,1]
	v_pk_fma_f32 v[168:169], v[14:15], v[90:91], v[158:159] op_sel_hi:[1,0,1]
	ds_read_b128 v[108:111], v25 offset:336
	v_pk_fma_f32 v[56:57], v[22:23], v[144:145], v[152:153] neg_lo:[0,0,1] neg_hi:[0,0,1]
	v_pk_fma_f32 v[170:171], v[30:31], v[118:119], v[156:157] op_sel:[0,1,0]
	ds_read_b128 v[112:115], v25 offset:352
	v_pk_fma_f32 v[166:167], v[34:35], v[82:83], v[160:161] op_sel:[0,1,0]
	v_mov_b32_e32 v57, v163
	ds_read_b128 v[116:119], v25 offset:368
	v_pk_fma_f32 v[172:173], v[42:43], v[90:91], v[168:169] op_sel:[0,1,0]
	ds_read_b128 v[72:75], v25 offset:384
	v_pk_fma_f32 v[174:175], v[0:1], v[84:85], v[166:167] op_sel_hi:[1,0,1]
	v_pk_add_f32 v[130:131], v[56:57], v[134:135]
	s_waitcnt lgkmcnt(7)
	v_pk_fma_f32 v[132:133], v[8:9], v[92:93], v[172:173] op_sel_hi:[1,0,1]
	s_waitcnt lgkmcnt(4)
	v_pk_fma_f32 v[176:177], v[12:13], v[104:105], 0 op_sel_hi:[1,0,0]
	v_pk_fma_f32 v[136:137], v[32:33], v[84:85], v[174:175] op_sel:[0,1,0]
	v_pk_mul_f32 v[138:139], v[46:47], v[130:131] op_sel:[0,1]
	v_pk_fma_f32 v[142:143], v[40:41], v[92:93], v[132:133] op_sel:[0,1,0]
	v_pk_fma_f32 v[164:165], v[44:45], v[104:105], v[176:177] op_sel:[0,1,0]
	v_pk_fma_f32 v[140:141], v[2:3], v[86:87], v[136:137] op_sel_hi:[1,0,1]
	v_pk_fma_f32 v[146:147], v[22:23], v[130:131], v[138:139] op_sel_hi:[1,0,1]
	v_pk_fma_f32 v[148:149], v[10:11], v[94:95], v[142:143] op_sel_hi:[1,0,1]
	v_pk_fma_f32 v[154:155], v[14:15], v[106:107], v[164:165] op_sel_hi:[1,0,1]
	ds_read_b128 v[76:79], v25 offset:400
	v_pk_fma_f32 v[56:57], v[22:23], v[130:131], v[138:139] neg_lo:[0,0,1] neg_hi:[0,0,1]
	v_pk_fma_f32 v[150:151], v[30:31], v[86:87], v[140:141] op_sel:[0,1,0]
	ds_read_b128 v[80:83], v25 offset:416
	v_mov_b32_e32 v57, v147
	ds_read_b128 v[84:87], v25 offset:432
	v_pk_fma_f32 v[158:159], v[38:39], v[94:95], v[148:149] op_sel:[0,1,0]
	v_pk_fma_f32 v[144:145], v[42:43], v[106:107], v[154:155] op_sel:[0,1,0]
	ds_read_b128 v[88:91], v25 offset:448
	v_pk_add_f32 v[152:153], v[56:57], v[170:171]
	v_pk_fma_f32 v[156:157], v[4:5], v[96:97], v[158:159] op_sel_hi:[1,0,1]
	s_waitcnt lgkmcnt(7)
	v_pk_fma_f32 v[160:161], v[8:9], v[108:109], v[144:145] op_sel_hi:[1,0,1]
	s_waitcnt lgkmcnt(4)
	v_pk_fma_f32 v[162:163], v[12:13], v[72:73], 0 op_sel_hi:[1,0,0]
	v_pk_mul_f32 v[168:169], v[46:47], v[152:153] op_sel:[0,1]
	v_pk_fma_f32 v[166:167], v[36:37], v[96:97], v[156:157] op_sel:[0,1,0]
	v_pk_fma_f32 v[134:135], v[40:41], v[108:109], v[160:161] op_sel:[0,1,0]
	v_pk_fma_f32 v[172:173], v[44:45], v[72:73], v[162:163] op_sel:[0,1,0]
	v_pk_fma_f32 v[174:175], v[22:23], v[152:153], v[168:169] op_sel_hi:[1,0,1]
	v_pk_fma_f32 v[132:133], v[6:7], v[98:99], v[166:167] op_sel_hi:[1,0,1]
	v_pk_fma_f32 v[176:177], v[10:11], v[110:111], v[134:135] op_sel_hi:[1,0,1]
	v_pk_fma_f32 v[136:137], v[14:15], v[74:75], v[172:173] op_sel_hi:[1,0,1]
	v_pk_fma_f32 v[56:57], v[22:23], v[152:153], v[168:169] neg_lo:[0,0,1] neg_hi:[0,0,1]
	v_mov_b32_e32 v57, v175
	v_pk_fma_f32 v[142:143], v[34:35], v[98:99], v[132:133] op_sel:[0,1,0]
	v_pk_fma_f32 v[164:165], v[38:39], v[110:111], v[176:177] op_sel:[0,1,0]
	v_pk_fma_f32 v[130:131], v[42:43], v[74:75], v[136:137] op_sel:[0,1,0]
	ds_read_b128 v[92:95], v25 offset:464
	v_pk_add_f32 v[138:139], v[56:57], v[150:151]
	v_pk_fma_f32 v[140:141], v[0:1], v[100:101], v[142:143] op_sel_hi:[1,0,1]
	v_pk_fma_f32 v[146:147], v[4:5], v[112:113], v[164:165] op_sel_hi:[1,0,1]
	s_waitcnt lgkmcnt(4)
	v_pk_fma_f32 v[148:149], v[8:9], v[76:77], v[130:131] op_sel_hi:[1,0,1]
	s_waitcnt lgkmcnt(1)
; #define LAS __attribute__((address_space(3)))
; template <bool PASSB>
; DI void s5_pass(const int tid, LAS unsigned char* lds, const P& p, int G, int c0) {
;     ...
;             for (int t = 0; t < 16; ++t) {
;                 float bur = 0.f, bui = 0.f;
; #pragma unroll
;                 for (int k = 0; k < 4; ++k) { const f32x4 u = *(const LAS f32x4*)(ubuf + t * 16 + k * 4);
; #pragma unroll
;                     for (int e = 0; e < 4; ++e) { bur += bre[4 * k + e] * u[e]; bui += bim[4 * k + e] * u[e]; } }
;                 const float nr = are * hre - aim * him + bur, ni = are * him + aim * hre + bui; hre = nr; him = ni;
;     ...
;         if (!PASSB) { float* he = hend + (((size_t)(b * 16 + g) * 8 + seg) * 64 + lane) * 2; he[0] = hre; he[1] = him; }
	v_pk_fma_f32 v[154:155], v[12:13], v[88:89], 0 op_sel_hi:[1,0,0]
	v_pk_mul_f32 v[170:171], v[46:47], v[138:139] op_sel:[0,1]
	v_pk_fma_f32 v[158:159], v[32:33], v[100:101], v[140:141] op_sel:[0,1,0]
	v_pk_fma_f32 v[144:145], v[36:37], v[112:113], v[146:147] op_sel:[0,1,0]
	v_pk_fma_f32 v[156:157], v[40:41], v[76:77], v[148:149] op_sel:[0,1,0]
	v_pk_fma_f32 v[160:161], v[44:45], v[88:89], v[154:155] op_sel:[0,1,0]
	v_pk_fma_f32 v[162:163], v[2:3], v[102:103], v[158:159] op_sel_hi:[1,0,1]
	v_pk_fma_f32 v[166:167], v[22:23], v[138:139], v[170:171] op_sel_hi:[1,0,1]
	v_pk_fma_f32 v[134:135], v[6:7], v[114:115], v[144:145] op_sel_hi:[1,0,1]
	v_pk_fma_f32 v[172:173], v[10:11], v[78:79], v[156:157] op_sel_hi:[1,0,1]
	v_pk_fma_f32 v[152:153], v[14:15], v[90:91], v[160:161] op_sel_hi:[1,0,1]
	v_pk_fma_f32 v[56:57], v[22:23], v[138:139], v[170:171] neg_lo:[0,0,1] neg_hi:[0,0,1]
	v_pk_fma_f32 v[168:169], v[30:31], v[102:103], v[162:163] op_sel:[0,1,0]
	v_mov_b32_e32 v57, v167
	v_pk_fma_f32 v[174:175], v[34:35], v[114:115], v[134:135] op_sel:[0,1,0]
	v_pk_fma_f32 v[132:133], v[38:39], v[78:79], v[172:173] op_sel:[0,1,0]
	v_pk_fma_f32 v[176:177], v[42:43], v[90:91], v[152:153] op_sel:[0,1,0]
	ds_read_b128 v[96:99], v25 offset:480
	v_pk_add_f32 v[136:137], v[56:57], v[168:169]
	v_pk_fma_f32 v[150:151], v[0:1], v[116:117], v[174:175] op_sel_hi:[1,0,1]
	v_pk_fma_f32 v[142:143], v[4:5], v[80:81], v[132:133] op_sel_hi:[1,0,1]
	s_waitcnt lgkmcnt(1)
	v_pk_fma_f32 v[164:165], v[8:9], v[92:93], v[176:177] op_sel_hi:[1,0,1]
	v_pk_mul_f32 v[130:131], v[46:47], v[136:137] op_sel:[0,1]
	v_pk_fma_f32 v[140:141], v[32:33], v[116:117], v[150:151] op_sel:[0,1,0]
	v_pk_fma_f32 v[146:147], v[36:37], v[80:81], v[142:143] op_sel:[0,1,0]
	v_pk_fma_f32 v[148:149], v[40:41], v[92:93], v[164:165] op_sel:[0,1,0]
	v_pk_fma_f32 v[154:155], v[2:3], v[118:119], v[140:141] op_sel_hi:[1,0,1]
	v_pk_fma_f32 v[158:159], v[22:23], v[136:137], v[130:131] op_sel_hi:[1,0,1]
	v_pk_fma_f32 v[144:145], v[6:7], v[82:83], v[146:147] op_sel_hi:[1,0,1]
	v_pk_fma_f32 v[156:157], v[10:11], v[94:95], v[148:149] op_sel_hi:[1,0,1]
	v_mov_b32_e32 v60, v95
	v_pk_fma_f32 v[56:57], v[22:23], v[136:137], v[130:131] neg_lo:[0,0,1] neg_hi:[0,0,1]
	v_pk_fma_f32 v[160:161], v[30:31], v[118:119], v[154:155] op_sel:[0,1,0]
	v_mov_b32_e32 v57, v159
	v_pk_fma_f32 v[138:139], v[34:35], v[82:83], v[144:145] op_sel:[0,1,0]
	v_pk_fma_f32 v[170:171], v[38:39], v[60:61], v[156:157] op_sel_hi:[1,0,1]
	ds_read_b128 v[100:103], v25 offset:496
	v_pk_add_f32 v[162:163], v[56:57], v[160:161]
	v_pk_fma_f32 v[166:167], v[0:1], v[84:85], v[138:139] op_sel_hi:[1,0,1]
	s_waitcnt lgkmcnt(1)
	v_pk_fma_f32 v[134:135], v[4:5], v[96:97], v[170:171] op_sel_hi:[1,0,1]
	v_pk_mul_f32 v[172:173], v[46:47], v[162:163] op_sel:[0,1]
	v_pk_fma_f32 v[152:153], v[32:33], v[84:85], v[166:167] op_sel:[0,1,0]
	v_pk_fma_f32 v[168:169], v[36:37], v[96:97], v[134:135] op_sel:[0,1,0]
	v_pk_fma_f32 v[174:175], v[22:23], v[162:163], v[172:173] op_sel_hi:[1,0,1]
	v_pk_fma_f32 v[132:133], v[2:3], v[86:87], v[152:153] op_sel_hi:[1,0,1]
	v_pk_fma_f32 v[176:177], v[6:7], v[98:99], v[168:169] op_sel_hi:[1,0,1]
	v_pk_fma_f32 v[56:57], v[22:23], v[162:163], v[172:173] neg_lo:[0,0,1] neg_hi:[0,0,1]
	v_pk_fma_f32 v[150:151], v[30:31], v[86:87], v[132:133] op_sel:[0,1,0]
	v_mov_b32_e32 v57, v175
	v_pk_fma_f32 v[142:143], v[34:35], v[98:99], v[176:177] op_sel:[0,1,0]
	v_pk_add_f32 v[164:165], v[56:57], v[150:151]
	s_waitcnt lgkmcnt(0)
	v_pk_fma_f32 v[140:141], v[0:1], v[100:101], v[142:143] op_sel_hi:[1,0,1]
	v_pk_mul_f32 v[146:147], v[46:47], v[164:165] op_sel:[0,1]
	v_pk_fma_f32 v[148:149], v[32:33], v[100:101], v[140:141] op_sel:[0,1,0]
	v_pk_fma_f32 v[136:137], v[22:23], v[164:165], v[146:147] op_sel_hi:[1,0,1]
	v_pk_fma_f32 v[130:131], v[2:3], v[102:103], v[148:149] op_sel_hi:[1,0,1]
	v_pk_fma_f32 v[56:57], v[22:23], v[164:165], v[146:147] neg_lo:[0,0,1] neg_hi:[0,0,1]
	v_mov_b32_e32 v57, v137
	v_pk_fma_f32 v[154:155], v[30:31], v[102:103], v[130:131] op_sel:[0,1,0]
	s_nop 0
	v_pk_add_f32 v[48:49], v[56:57], v[154:155]
	s_cbranch_scc1 .LBB0_588
	s_waitcnt lgkmcnt(0)
	s_add_i32 s6, s6, 1
	s_cmp_eq_u32 s6, 16
	s_cbranch_scc0 .LBB0_585
	v_lshl_add_u32 v0, v24, 4, s5
	v_ashrrev_i32_e32 v1, 31, v0
	v_readlane_b32 s0, v253, 16
	v_lshlrev_b64 v[0:1], 12, v[0:1]
	s_add_i32 s4, s4, s0
	v_lshl_add_u64 v[0:1], v[20:21], 0, v[0:1]
	s_cmpk_gt_i32 s4, 0x1ff
	v_readlane_b32 s1, v253, 17
	global_store_dwordx2 v[0:1], v[48:49], off
	s_cbranch_scc0 .LBB0_584
